# inproj epilogue: HQKV tiles with conv-state rows also take the fast path (f32 tail quads stored under an exec mask)
# baseline (speedup 1.0000x reference)
.LBB0_1001:
	s_or_b64 exec, exec, s[0:1]
	s_mov_b32 s53, 0
	s_mov_b32 s62, 0
	s_cmp_lt_u32 s80, 2
	s_cbranch_scc1 .Lipf_hq
	s_sub_u32 s0, s80, 3
	s_cmp_lt_u32 s0, 2
	s_cbranch_scc1 .Lipf_hqi
	s_sub_u32 s0, s80, 6
	s_cmp_lt_u32 s0, 5
	s_cbranch_scc1 .Lipf_hqkv
	s_cmp_eq_u32 s80, 12
	s_cbranch_scc1 .Lipf_hgb
	s_sub_u32 s0, s80, 14
	s_cmp_lt_u32 s0, 7
	s_cbranch_scc1 .Lipf_hg
	s_cmp_eq_u32 s80, 11
	s_cbranch_scc1 .Lipg_11
	s_cmp_eq_u32 s80, 13
	s_cbranch_scc1 .Lipg_13
	s_cmp_eq_u32 s80, 21
	s_cbranch_scc1 .Lipg_21
	s_cmp_eq_u32 s80, 5
	s_cbranch_scc1 .Lipg_5
	s_cmp_eq_u32 s80, 2
	s_cbranch_scc1 .Lipk
	s_branch .Lipf_slow

.Lipf_hqkv:
	s_cmpk_gt_i32 s81, 0x7f
	s_cselect_b32 s62, 2, 0
	s_cbranch_scc1 .Lipf_hqkv2
	s_and_b32 s0, s81, 15
	s_cmp_eq_u32 s0, 15
	s_cselect_b32 s62, 1, 0
	.Lipf_hqkv2:
	s_mov_b32 s44, 0xa180000
	s_movk_i32 s45, 0x548
	s_movk_i32 s52, 0xc00
	s_branch .Lipf_common

.Lipf_common:
	s_lshl_b32 s54, s80, 8
	s_sub_u32 s45, s54, s45
	s_lshl_b32 s0, s45, 1
	s_add_u32 s44, s44, s0
	s_add_u32 s56, s12, s44
	s_addc_u32 s57, s13, 0
	s_lshl_b32 s60, s81, 8
	s_mov_b32 s43, 0
	v_add_u32_e32 v176, s60, v150
	v_lshrrev_b32_e32 v178, 4, v219
	v_and_b32_e32 v179, 1, v178
	v_lshrrev_b32_e32 v178, 1, v178
	v_lshl_add_u32 v178, v179, 1, v178
	v_lshlrev_b32_e32 v178, 4, v178
	v_bfe_u32 v179, v211, 6, 2
	v_lshl_add_u32 v158, v179, 6, v178
	v_mov_b32_e32 v159, 0
	s_nop 7
	s_nop 7
	v_mad_u64_u32 v[152:153], s[58:59], v176, s52, v[158:159]
	v_lshl_add_u64 v[152:153], v[152:153], 0, s[56:57]
	s_cmp_lg_u32 s62, 0
	s_cbranch_scc1 .Lipf_ct
	s_cmp_eq_u32 s53, 0
	s_cbranch_scc1 .Lipf_plain
	v_add_u32_e32 v178, s45, v135
	v_mov_b32_e32 v179, 0
	v_lshl_add_u64 v[178:179], v[178:179], 2, s[10:11]
	global_load_dwordx4 v[160:163], v[178:179], off offset:0
	global_load_dwordx4 v[164:167], v[178:179], off offset:64
	global_load_dwordx4 v[168:171], v[178:179], off offset:512
	global_load_dwordx4 v[172:175], v[178:179], off offset:576
	s_waitcnt vmcnt(0)
	v_mov_b32_e32 v154, v152
	v_mov_b32_e32 v155, v153
	v_add_f32_e32 v130, v130, v160
	v_add_f32_e32 v131, v131, v161
	v_add_f32_e32 v132, v132, v162
	v_add_f32_e32 v133, v133, v163
	v_add_f32_e32 v94, v94, v164
	v_add_f32_e32 v95, v95, v165
	v_add_f32_e32 v96, v96, v166
	v_add_f32_e32 v97, v97, v167
	v_mul_f32_e32 v130, 0xbfb8aa3b, v130
	v_mul_f32_e32 v131, 0xbfb8aa3b, v131
	v_mul_f32_e32 v132, 0xbfb8aa3b, v132
	v_mul_f32_e32 v133, 0xbfb8aa3b, v133
	v_mul_f32_e32 v94, 0xbfb8aa3b, v94
	v_mul_f32_e32 v95, 0xbfb8aa3b, v95
	v_mul_f32_e32 v96, 0xbfb8aa3b, v96
	v_mul_f32_e32 v97, 0xbfb8aa3b, v97
	v_exp_f32_e32 v130, v130
	v_exp_f32_e32 v131, v131
	v_exp_f32_e32 v132, v132
	v_exp_f32_e32 v133, v133
	v_exp_f32_e32 v94, v94
	v_exp_f32_e32 v95, v95
	v_exp_f32_e32 v96, v96
	v_exp_f32_e32 v97, v97
	v_add_f32_e32 v130, 1.0, v130
	v_add_f32_e32 v131, 1.0, v131
	v_add_f32_e32 v132, 1.0, v132
	v_add_f32_e32 v133, 1.0, v133
	v_add_f32_e32 v94, 1.0, v94
	v_add_f32_e32 v95, 1.0, v95
	v_add_f32_e32 v96, 1.0, v96
	v_add_f32_e32 v97, 1.0, v97
	v_rcp_f32_e32 v130, v130
	v_rcp_f32_e32 v131, v131
	v_rcp_f32_e32 v132, v132
	v_rcp_f32_e32 v133, v133
	v_rcp_f32_e32 v94, v94
	v_rcp_f32_e32 v95, v95
	v_rcp_f32_e32 v96, v96
	v_rcp_f32_e32 v97, v97
	v_add_f32_e32 v62, v62, v168
	v_add_f32_e32 v63, v63, v169
	v_add_f32_e32 v64, v64, v170
	v_add_f32_e32 v65, v65, v171
	v_add_f32_e32 v30, v30, v172
	v_add_f32_e32 v31, v31, v173
	v_add_f32_e32 v32, v32, v174
	v_add_f32_e32 v33, v33, v175
	v_mul_f32_e32 v62, 0xbfb8aa3b, v62
	v_mul_f32_e32 v63, 0xbfb8aa3b, v63
	v_mul_f32_e32 v64, 0xbfb8aa3b, v64
	v_mul_f32_e32 v65, 0xbfb8aa3b, v65
	v_mul_f32_e32 v30, 0xbfb8aa3b, v30
	v_mul_f32_e32 v31, 0xbfb8aa3b, v31
	v_mul_f32_e32 v32, 0xbfb8aa3b, v32
	v_mul_f32_e32 v33, 0xbfb8aa3b, v33
	v_exp_f32_e32 v62, v62
	v_exp_f32_e32 v63, v63
	v_exp_f32_e32 v64, v64
	v_exp_f32_e32 v65, v65
	v_exp_f32_e32 v30, v30
	v_exp_f32_e32 v31, v31
	v_exp_f32_e32 v32, v32
	v_exp_f32_e32 v33, v33
	v_add_f32_e32 v62, 1.0, v62
	v_add_f32_e32 v63, 1.0, v63
	v_add_f32_e32 v64, 1.0, v64
	v_add_f32_e32 v65, 1.0, v65
	v_add_f32_e32 v30, 1.0, v30
	v_add_f32_e32 v31, 1.0, v31
	v_add_f32_e32 v32, 1.0, v32
	v_add_f32_e32 v33, 1.0, v33
	v_rcp_f32_e32 v62, v62
	v_rcp_f32_e32 v63, v63
	v_rcp_f32_e32 v64, v64
	v_rcp_f32_e32 v65, v65
	v_rcp_f32_e32 v30, v30
	v_rcp_f32_e32 v31, v31
	v_rcp_f32_e32 v32, v32
	v_rcp_f32_e32 v33, v33
	v_cvt_pk_bf16_f32 v130, v130, v131
	v_cvt_pk_bf16_f32 v131, v132, v133
	v_cvt_pk_bf16_f32 v132, v94, v95
	v_cvt_pk_bf16_f32 v133, v96, v97
	v_cvt_pk_bf16_f32 v62, v62, v63
	v_cvt_pk_bf16_f32 v63, v64, v65
	v_cvt_pk_bf16_f32 v64, v30, v31
	v_cvt_pk_bf16_f32 v65, v32, v33
	v_permlane16_swap_b32_e32 v130, v132
	v_permlane16_swap_b32_e32 v131, v133
	v_permlane16_swap_b32_e32 v62, v64
	v_permlane16_swap_b32_e32 v63, v65
	global_store_dwordx4 v[154:155], v[130:133], off offset:0
	global_store_dwordx4 v[154:155], v[62:65], off offset:256
	s_mul_i32 s42, s52, 16
	v_lshl_add_u64 v[156:157], v[152:153], 0, s[42:43]
	v_add_f32_e32 v126, v126, v160
	v_add_f32_e32 v127, v127, v161
	v_add_f32_e32 v128, v128, v162
	v_add_f32_e32 v129, v129, v163
	v_add_f32_e32 v90, v90, v164
	v_add_f32_e32 v91, v91, v165
	v_add_f32_e32 v92, v92, v166
	v_add_f32_e32 v93, v93, v167
	v_mul_f32_e32 v126, 0xbfb8aa3b, v126
	v_mul_f32_e32 v127, 0xbfb8aa3b, v127
	v_mul_f32_e32 v128, 0xbfb8aa3b, v128
	v_mul_f32_e32 v129, 0xbfb8aa3b, v129
	v_mul_f32_e32 v90, 0xbfb8aa3b, v90
	v_mul_f32_e32 v91, 0xbfb8aa3b, v91
	v_mul_f32_e32 v92, 0xbfb8aa3b, v92
	v_mul_f32_e32 v93, 0xbfb8aa3b, v93
	v_exp_f32_e32 v126, v126
	v_exp_f32_e32 v127, v127
	v_exp_f32_e32 v128, v128
	v_exp_f32_e32 v129, v129
	v_exp_f32_e32 v90, v90
	v_exp_f32_e32 v91, v91
	v_exp_f32_e32 v92, v92
	v_exp_f32_e32 v93, v93
	v_add_f32_e32 v126, 1.0, v126
	v_add_f32_e32 v127, 1.0, v127
	v_add_f32_e32 v128, 1.0, v128
	v_add_f32_e32 v129, 1.0, v129
	v_add_f32_e32 v90, 1.0, v90
	v_add_f32_e32 v91, 1.0, v91
	v_add_f32_e32 v92, 1.0, v92
	v_add_f32_e32 v93, 1.0, v93
	v_rcp_f32_e32 v126, v126
	v_rcp_f32_e32 v127, v127
	v_rcp_f32_e32 v128, v128
	v_rcp_f32_e32 v129, v129
	v_rcp_f32_e32 v90, v90
	v_rcp_f32_e32 v91, v91
	v_rcp_f32_e32 v92, v92
	v_rcp_f32_e32 v93, v93
	v_add_f32_e32 v58, v58, v168
	v_add_f32_e32 v59, v59, v169
	v_add_f32_e32 v60, v60, v170
	v_add_f32_e32 v61, v61, v171
	v_add_f32_e32 v26, v26, v172
	v_add_f32_e32 v27, v27, v173
	v_add_f32_e32 v28, v28, v174
	v_add_f32_e32 v29, v29, v175
	v_mul_f32_e32 v58, 0xbfb8aa3b, v58
	v_mul_f32_e32 v59, 0xbfb8aa3b, v59
	v_mul_f32_e32 v60, 0xbfb8aa3b, v60
	v_mul_f32_e32 v61, 0xbfb8aa3b, v61
	v_mul_f32_e32 v26, 0xbfb8aa3b, v26
	v_mul_f32_e32 v27, 0xbfb8aa3b, v27
	v_mul_f32_e32 v28, 0xbfb8aa3b, v28
	v_mul_f32_e32 v29, 0xbfb8aa3b, v29
	v_exp_f32_e32 v58, v58
	v_exp_f32_e32 v59, v59
	v_exp_f32_e32 v60, v60
	v_exp_f32_e32 v61, v61
	v_exp_f32_e32 v26, v26
	v_exp_f32_e32 v27, v27
	v_exp_f32_e32 v28, v28
	v_exp_f32_e32 v29, v29
	v_add_f32_e32 v58, 1.0, v58
	v_add_f32_e32 v59, 1.0, v59
	v_add_f32_e32 v60, 1.0, v60
	v_add_f32_e32 v61, 1.0, v61
	v_add_f32_e32 v26, 1.0, v26
	v_add_f32_e32 v27, 1.0, v27
	v_add_f32_e32 v28, 1.0, v28
	v_add_f32_e32 v29, 1.0, v29
	v_rcp_f32_e32 v58, v58
	v_rcp_f32_e32 v59, v59
	v_rcp_f32_e32 v60, v60
	v_rcp_f32_e32 v61, v61
	v_rcp_f32_e32 v26, v26
	v_rcp_f32_e32 v27, v27
	v_rcp_f32_e32 v28, v28
	v_rcp_f32_e32 v29, v29
	v_cvt_pk_bf16_f32 v126, v126, v127
	v_cvt_pk_bf16_f32 v127, v128, v129
	v_cvt_pk_bf16_f32 v128, v90, v91
	v_cvt_pk_bf16_f32 v129, v92, v93
	v_cvt_pk_bf16_f32 v58, v58, v59
	v_cvt_pk_bf16_f32 v59, v60, v61
	v_cvt_pk_bf16_f32 v60, v26, v27
	v_cvt_pk_bf16_f32 v61, v28, v29
	v_permlane16_swap_b32_e32 v126, v128
	v_permlane16_swap_b32_e32 v127, v129
	v_permlane16_swap_b32_e32 v58, v60
	v_permlane16_swap_b32_e32 v59, v61
	global_store_dwordx4 v[156:157], v[126:129], off offset:0
	global_store_dwordx4 v[156:157], v[58:61], off offset:256
	s_mul_i32 s42, s52, 32
	v_lshl_add_u64 v[154:155], v[152:153], 0, s[42:43]
	v_add_f32_e32 v122, v122, v160
	v_add_f32_e32 v123, v123, v161
	v_add_f32_e32 v124, v124, v162
	v_add_f32_e32 v125, v125, v163
	v_add_f32_e32 v86, v86, v164
	v_add_f32_e32 v87, v87, v165
	v_add_f32_e32 v88, v88, v166
	v_add_f32_e32 v89, v89, v167
	v_mul_f32_e32 v122, 0xbfb8aa3b, v122
	v_mul_f32_e32 v123, 0xbfb8aa3b, v123
	v_mul_f32_e32 v124, 0xbfb8aa3b, v124
	v_mul_f32_e32 v125, 0xbfb8aa3b, v125
	v_mul_f32_e32 v86, 0xbfb8aa3b, v86
	v_mul_f32_e32 v87, 0xbfb8aa3b, v87
	v_mul_f32_e32 v88, 0xbfb8aa3b, v88
	v_mul_f32_e32 v89, 0xbfb8aa3b, v89
	v_exp_f32_e32 v122, v122
	v_exp_f32_e32 v123, v123
	v_exp_f32_e32 v124, v124
	v_exp_f32_e32 v125, v125
	v_exp_f32_e32 v86, v86
	v_exp_f32_e32 v87, v87
	v_exp_f32_e32 v88, v88
	v_exp_f32_e32 v89, v89
	v_add_f32_e32 v122, 1.0, v122
	v_add_f32_e32 v123, 1.0, v123
	v_add_f32_e32 v124, 1.0, v124
	v_add_f32_e32 v125, 1.0, v125
	v_add_f32_e32 v86, 1.0, v86
	v_add_f32_e32 v87, 1.0, v87
	v_add_f32_e32 v88, 1.0, v88
	v_add_f32_e32 v89, 1.0, v89
	v_rcp_f32_e32 v122, v122
	v_rcp_f32_e32 v123, v123
	v_rcp_f32_e32 v124, v124
	v_rcp_f32_e32 v125, v125
	v_rcp_f32_e32 v86, v86
	v_rcp_f32_e32 v87, v87
	v_rcp_f32_e32 v88, v88
	v_rcp_f32_e32 v89, v89
	v_add_f32_e32 v54, v54, v168
	v_add_f32_e32 v55, v55, v169
	v_add_f32_e32 v56, v56, v170
	v_add_f32_e32 v57, v57, v171
	v_add_f32_e32 v22, v22, v172
	v_add_f32_e32 v23, v23, v173
	v_add_f32_e32 v24, v24, v174
	v_add_f32_e32 v25, v25, v175
	v_mul_f32_e32 v54, 0xbfb8aa3b, v54
	v_mul_f32_e32 v55, 0xbfb8aa3b, v55
	v_mul_f32_e32 v56, 0xbfb8aa3b, v56
	v_mul_f32_e32 v57, 0xbfb8aa3b, v57
	v_mul_f32_e32 v22, 0xbfb8aa3b, v22
	v_mul_f32_e32 v23, 0xbfb8aa3b, v23
	v_mul_f32_e32 v24, 0xbfb8aa3b, v24
	v_mul_f32_e32 v25, 0xbfb8aa3b, v25
	v_exp_f32_e32 v54, v54
	v_exp_f32_e32 v55, v55
	v_exp_f32_e32 v56, v56
	v_exp_f32_e32 v57, v57
	v_exp_f32_e32 v22, v22
	v_exp_f32_e32 v23, v23
	v_exp_f32_e32 v24, v24
	v_exp_f32_e32 v25, v25
	v_add_f32_e32 v54, 1.0, v54
	v_add_f32_e32 v55, 1.0, v55
	v_add_f32_e32 v56, 1.0, v56
	v_add_f32_e32 v57, 1.0, v57
	v_add_f32_e32 v22, 1.0, v22
	v_add_f32_e32 v23, 1.0, v23
	v_add_f32_e32 v24, 1.0, v24
	v_add_f32_e32 v25, 1.0, v25
	v_rcp_f32_e32 v54, v54
	v_rcp_f32_e32 v55, v55
	v_rcp_f32_e32 v56, v56
	v_rcp_f32_e32 v57, v57
	v_rcp_f32_e32 v22, v22
	v_rcp_f32_e32 v23, v23
	v_rcp_f32_e32 v24, v24
	v_rcp_f32_e32 v25, v25
	v_cvt_pk_bf16_f32 v122, v122, v123
	v_cvt_pk_bf16_f32 v123, v124, v125
	v_cvt_pk_bf16_f32 v124, v86, v87
	v_cvt_pk_bf16_f32 v125, v88, v89
	v_cvt_pk_bf16_f32 v54, v54, v55
	v_cvt_pk_bf16_f32 v55, v56, v57
	v_cvt_pk_bf16_f32 v56, v22, v23
	v_cvt_pk_bf16_f32 v57, v24, v25
	v_permlane16_swap_b32_e32 v122, v124
	v_permlane16_swap_b32_e32 v123, v125
	v_permlane16_swap_b32_e32 v54, v56
	v_permlane16_swap_b32_e32 v55, v57
	global_store_dwordx4 v[154:155], v[122:125], off offset:0
	global_store_dwordx4 v[154:155], v[54:57], off offset:256
	s_mul_i32 s42, s52, 48
	v_lshl_add_u64 v[156:157], v[152:153], 0, s[42:43]
	v_add_f32_e32 v118, v118, v160
	v_add_f32_e32 v119, v119, v161
	v_add_f32_e32 v120, v120, v162
	v_add_f32_e32 v121, v121, v163
	v_add_f32_e32 v82, v82, v164
	v_add_f32_e32 v83, v83, v165
	v_add_f32_e32 v84, v84, v166
	v_add_f32_e32 v85, v85, v167
	v_mul_f32_e32 v118, 0xbfb8aa3b, v118
	v_mul_f32_e32 v119, 0xbfb8aa3b, v119
	v_mul_f32_e32 v120, 0xbfb8aa3b, v120
	v_mul_f32_e32 v121, 0xbfb8aa3b, v121
	v_mul_f32_e32 v82, 0xbfb8aa3b, v82
	v_mul_f32_e32 v83, 0xbfb8aa3b, v83
	v_mul_f32_e32 v84, 0xbfb8aa3b, v84
	v_mul_f32_e32 v85, 0xbfb8aa3b, v85
	v_exp_f32_e32 v118, v118
	v_exp_f32_e32 v119, v119
	v_exp_f32_e32 v120, v120
	v_exp_f32_e32 v121, v121
	v_exp_f32_e32 v82, v82
	v_exp_f32_e32 v83, v83
	v_exp_f32_e32 v84, v84
	v_exp_f32_e32 v85, v85
	v_add_f32_e32 v118, 1.0, v118
	v_add_f32_e32 v119, 1.0, v119
	v_add_f32_e32 v120, 1.0, v120
	v_add_f32_e32 v121, 1.0, v121
	v_add_f32_e32 v82, 1.0, v82
	v_add_f32_e32 v83, 1.0, v83
	v_add_f32_e32 v84, 1.0, v84
	v_add_f32_e32 v85, 1.0, v85
	v_rcp_f32_e32 v118, v118
	v_rcp_f32_e32 v119, v119
	v_rcp_f32_e32 v120, v120
	v_rcp_f32_e32 v121, v121
	v_rcp_f32_e32 v82, v82
	v_rcp_f32_e32 v83, v83
	v_rcp_f32_e32 v84, v84
	v_rcp_f32_e32 v85, v85
	v_add_f32_e32 v50, v50, v168
	v_add_f32_e32 v51, v51, v169
	v_add_f32_e32 v52, v52, v170
	v_add_f32_e32 v53, v53, v171
	v_add_f32_e32 v18, v18, v172
	v_add_f32_e32 v19, v19, v173
	v_add_f32_e32 v20, v20, v174
	v_add_f32_e32 v21, v21, v175
	v_mul_f32_e32 v50, 0xbfb8aa3b, v50
	v_mul_f32_e32 v51, 0xbfb8aa3b, v51
	v_mul_f32_e32 v52, 0xbfb8aa3b, v52
	v_mul_f32_e32 v53, 0xbfb8aa3b, v53
	v_mul_f32_e32 v18, 0xbfb8aa3b, v18
	v_mul_f32_e32 v19, 0xbfb8aa3b, v19
	v_mul_f32_e32 v20, 0xbfb8aa3b, v20
	v_mul_f32_e32 v21, 0xbfb8aa3b, v21
	v_exp_f32_e32 v50, v50
	v_exp_f32_e32 v51, v51
	v_exp_f32_e32 v52, v52
	v_exp_f32_e32 v53, v53
	v_exp_f32_e32 v18, v18
	v_exp_f32_e32 v19, v19
	v_exp_f32_e32 v20, v20
	v_exp_f32_e32 v21, v21
	v_add_f32_e32 v50, 1.0, v50
	v_add_f32_e32 v51, 1.0, v51
	v_add_f32_e32 v52, 1.0, v52
	v_add_f32_e32 v53, 1.0, v53
	v_add_f32_e32 v18, 1.0, v18
	v_add_f32_e32 v19, 1.0, v19
	v_add_f32_e32 v20, 1.0, v20
	v_add_f32_e32 v21, 1.0, v21
	v_rcp_f32_e32 v50, v50
	v_rcp_f32_e32 v51, v51
	v_rcp_f32_e32 v52, v52
	v_rcp_f32_e32 v53, v53
	v_rcp_f32_e32 v18, v18
	v_rcp_f32_e32 v19, v19
	v_rcp_f32_e32 v20, v20
	v_rcp_f32_e32 v21, v21
	v_cvt_pk_bf16_f32 v118, v118, v119
	v_cvt_pk_bf16_f32 v119, v120, v121
	v_cvt_pk_bf16_f32 v120, v82, v83
	v_cvt_pk_bf16_f32 v121, v84, v85
	v_cvt_pk_bf16_f32 v50, v50, v51
	v_cvt_pk_bf16_f32 v51, v52, v53
	v_cvt_pk_bf16_f32 v52, v18, v19
	v_cvt_pk_bf16_f32 v53, v20, v21
	v_permlane16_swap_b32_e32 v118, v120
	v_permlane16_swap_b32_e32 v119, v121
	v_permlane16_swap_b32_e32 v50, v52
	v_permlane16_swap_b32_e32 v51, v53
	global_store_dwordx4 v[156:157], v[118:121], off offset:0
	global_store_dwordx4 v[156:157], v[50:53], off offset:256
	s_mul_i32 s42, s52, 128
	v_lshl_add_u64 v[154:155], v[152:153], 0, s[42:43]
	v_add_f32_e32 v114, v114, v160
	v_add_f32_e32 v115, v115, v161
	v_add_f32_e32 v116, v116, v162
	v_add_f32_e32 v117, v117, v163
	v_add_f32_e32 v78, v78, v164
	v_add_f32_e32 v79, v79, v165
	v_add_f32_e32 v80, v80, v166
	v_add_f32_e32 v81, v81, v167
	v_mul_f32_e32 v114, 0xbfb8aa3b, v114
	v_mul_f32_e32 v115, 0xbfb8aa3b, v115
	v_mul_f32_e32 v116, 0xbfb8aa3b, v116
	v_mul_f32_e32 v117, 0xbfb8aa3b, v117
	v_mul_f32_e32 v78, 0xbfb8aa3b, v78
	v_mul_f32_e32 v79, 0xbfb8aa3b, v79
	v_mul_f32_e32 v80, 0xbfb8aa3b, v80
	v_mul_f32_e32 v81, 0xbfb8aa3b, v81
	v_exp_f32_e32 v114, v114
	v_exp_f32_e32 v115, v115
	v_exp_f32_e32 v116, v116
	v_exp_f32_e32 v117, v117
	v_exp_f32_e32 v78, v78
	v_exp_f32_e32 v79, v79
	v_exp_f32_e32 v80, v80
	v_exp_f32_e32 v81, v81
	v_add_f32_e32 v114, 1.0, v114
	v_add_f32_e32 v115, 1.0, v115
	v_add_f32_e32 v116, 1.0, v116
	v_add_f32_e32 v117, 1.0, v117
	v_add_f32_e32 v78, 1.0, v78
	v_add_f32_e32 v79, 1.0, v79
	v_add_f32_e32 v80, 1.0, v80
	v_add_f32_e32 v81, 1.0, v81
	v_rcp_f32_e32 v114, v114
	v_rcp_f32_e32 v115, v115
	v_rcp_f32_e32 v116, v116
	v_rcp_f32_e32 v117, v117
	v_rcp_f32_e32 v78, v78
	v_rcp_f32_e32 v79, v79
	v_rcp_f32_e32 v80, v80
	v_rcp_f32_e32 v81, v81
	v_add_f32_e32 v46, v46, v168
	v_add_f32_e32 v47, v47, v169
	v_add_f32_e32 v48, v48, v170
	v_add_f32_e32 v49, v49, v171
	v_add_f32_e32 v14, v14, v172
	v_add_f32_e32 v15, v15, v173
	v_add_f32_e32 v16, v16, v174
	v_add_f32_e32 v17, v17, v175
	v_mul_f32_e32 v46, 0xbfb8aa3b, v46
	v_mul_f32_e32 v47, 0xbfb8aa3b, v47
	v_mul_f32_e32 v48, 0xbfb8aa3b, v48
	v_mul_f32_e32 v49, 0xbfb8aa3b, v49
	v_mul_f32_e32 v14, 0xbfb8aa3b, v14
	v_mul_f32_e32 v15, 0xbfb8aa3b, v15
	v_mul_f32_e32 v16, 0xbfb8aa3b, v16
	v_mul_f32_e32 v17, 0xbfb8aa3b, v17
	v_exp_f32_e32 v46, v46
	v_exp_f32_e32 v47, v47
	v_exp_f32_e32 v48, v48
	v_exp_f32_e32 v49, v49
	v_exp_f32_e32 v14, v14
	v_exp_f32_e32 v15, v15
	v_exp_f32_e32 v16, v16
	v_exp_f32_e32 v17, v17
	v_add_f32_e32 v46, 1.0, v46
	v_add_f32_e32 v47, 1.0, v47
	v_add_f32_e32 v48, 1.0, v48
	v_add_f32_e32 v49, 1.0, v49
	v_add_f32_e32 v14, 1.0, v14
	v_add_f32_e32 v15, 1.0, v15
	v_add_f32_e32 v16, 1.0, v16
	v_add_f32_e32 v17, 1.0, v17
	v_rcp_f32_e32 v46, v46
	v_rcp_f32_e32 v47, v47
	v_rcp_f32_e32 v48, v48
	v_rcp_f32_e32 v49, v49
	v_rcp_f32_e32 v14, v14
	v_rcp_f32_e32 v15, v15
	v_rcp_f32_e32 v16, v16
	v_rcp_f32_e32 v17, v17
	v_cvt_pk_bf16_f32 v114, v114, v115
	v_cvt_pk_bf16_f32 v115, v116, v117
	v_cvt_pk_bf16_f32 v116, v78, v79
	v_cvt_pk_bf16_f32 v117, v80, v81
	v_cvt_pk_bf16_f32 v46, v46, v47
	v_cvt_pk_bf16_f32 v47, v48, v49
	v_cvt_pk_bf16_f32 v48, v14, v15
	v_cvt_pk_bf16_f32 v49, v16, v17
	v_permlane16_swap_b32_e32 v114, v116
	v_permlane16_swap_b32_e32 v115, v117
	v_permlane16_swap_b32_e32 v46, v48
	v_permlane16_swap_b32_e32 v47, v49
	global_store_dwordx4 v[154:155], v[114:117], off offset:0
	global_store_dwordx4 v[154:155], v[46:49], off offset:256
	s_mul_i32 s42, s52, 144
	v_lshl_add_u64 v[156:157], v[152:153], 0, s[42:43]
	v_add_f32_e32 v106, v106, v160
	v_add_f32_e32 v107, v107, v161
	v_add_f32_e32 v108, v108, v162
	v_add_f32_e32 v109, v109, v163
	v_add_f32_e32 v74, v74, v164
	v_add_f32_e32 v75, v75, v165
	v_add_f32_e32 v76, v76, v166
	v_add_f32_e32 v77, v77, v167
	v_mul_f32_e32 v106, 0xbfb8aa3b, v106
	v_mul_f32_e32 v107, 0xbfb8aa3b, v107
	v_mul_f32_e32 v108, 0xbfb8aa3b, v108
	v_mul_f32_e32 v109, 0xbfb8aa3b, v109
	v_mul_f32_e32 v74, 0xbfb8aa3b, v74
	v_mul_f32_e32 v75, 0xbfb8aa3b, v75
	v_mul_f32_e32 v76, 0xbfb8aa3b, v76
	v_mul_f32_e32 v77, 0xbfb8aa3b, v77
	v_exp_f32_e32 v106, v106
	v_exp_f32_e32 v107, v107
	v_exp_f32_e32 v108, v108
	v_exp_f32_e32 v109, v109
	v_exp_f32_e32 v74, v74
	v_exp_f32_e32 v75, v75
	v_exp_f32_e32 v76, v76
	v_exp_f32_e32 v77, v77
	v_add_f32_e32 v106, 1.0, v106
	v_add_f32_e32 v107, 1.0, v107
	v_add_f32_e32 v108, 1.0, v108
	v_add_f32_e32 v109, 1.0, v109
	v_add_f32_e32 v74, 1.0, v74
	v_add_f32_e32 v75, 1.0, v75
	v_add_f32_e32 v76, 1.0, v76
	v_add_f32_e32 v77, 1.0, v77
	v_rcp_f32_e32 v106, v106
	v_rcp_f32_e32 v107, v107
	v_rcp_f32_e32 v108, v108
	v_rcp_f32_e32 v109, v109
	v_rcp_f32_e32 v74, v74
	v_rcp_f32_e32 v75, v75
	v_rcp_f32_e32 v76, v76
	v_rcp_f32_e32 v77, v77
	v_add_f32_e32 v42, v42, v168
	v_add_f32_e32 v43, v43, v169
	v_add_f32_e32 v44, v44, v170
	v_add_f32_e32 v45, v45, v171
	v_add_f32_e32 v10, v10, v172
	v_add_f32_e32 v11, v11, v173
	v_add_f32_e32 v12, v12, v174
	v_add_f32_e32 v13, v13, v175
	v_mul_f32_e32 v42, 0xbfb8aa3b, v42
	v_mul_f32_e32 v43, 0xbfb8aa3b, v43
	v_mul_f32_e32 v44, 0xbfb8aa3b, v44
	v_mul_f32_e32 v45, 0xbfb8aa3b, v45
	v_mul_f32_e32 v10, 0xbfb8aa3b, v10
	v_mul_f32_e32 v11, 0xbfb8aa3b, v11
	v_mul_f32_e32 v12, 0xbfb8aa3b, v12
	v_mul_f32_e32 v13, 0xbfb8aa3b, v13
	v_exp_f32_e32 v42, v42
	v_exp_f32_e32 v43, v43
	v_exp_f32_e32 v44, v44
	v_exp_f32_e32 v45, v45
	v_exp_f32_e32 v10, v10
	v_exp_f32_e32 v11, v11
	v_exp_f32_e32 v12, v12
	v_exp_f32_e32 v13, v13
	v_add_f32_e32 v42, 1.0, v42
	v_add_f32_e32 v43, 1.0, v43
	v_add_f32_e32 v44, 1.0, v44
	v_add_f32_e32 v45, 1.0, v45
	v_add_f32_e32 v10, 1.0, v10
	v_add_f32_e32 v11, 1.0, v11
	v_add_f32_e32 v12, 1.0, v12
	v_add_f32_e32 v13, 1.0, v13
	v_rcp_f32_e32 v42, v42
	v_rcp_f32_e32 v43, v43
	v_rcp_f32_e32 v44, v44
	v_rcp_f32_e32 v45, v45
	v_rcp_f32_e32 v10, v10
	v_rcp_f32_e32 v11, v11
	v_rcp_f32_e32 v12, v12
	v_rcp_f32_e32 v13, v13
	v_cvt_pk_bf16_f32 v106, v106, v107
	v_cvt_pk_bf16_f32 v107, v108, v109
	v_cvt_pk_bf16_f32 v108, v74, v75
	v_cvt_pk_bf16_f32 v109, v76, v77
	v_cvt_pk_bf16_f32 v42, v42, v43
	v_cvt_pk_bf16_f32 v43, v44, v45
	v_cvt_pk_bf16_f32 v44, v10, v11
	v_cvt_pk_bf16_f32 v45, v12, v13
	v_permlane16_swap_b32_e32 v106, v108
	v_permlane16_swap_b32_e32 v107, v109
	v_permlane16_swap_b32_e32 v42, v44
	v_permlane16_swap_b32_e32 v43, v45
	global_store_dwordx4 v[156:157], v[106:109], off offset:0
	global_store_dwordx4 v[156:157], v[42:45], off offset:256
	s_mul_i32 s42, s52, 160
	v_lshl_add_u64 v[154:155], v[152:153], 0, s[42:43]
	v_add_f32_e32 v102, v102, v160
	v_add_f32_e32 v103, v103, v161
	v_add_f32_e32 v104, v104, v162
	v_add_f32_e32 v105, v105, v163
	v_add_f32_e32 v70, v70, v164
	v_add_f32_e32 v71, v71, v165
	v_add_f32_e32 v72, v72, v166
	v_add_f32_e32 v73, v73, v167
	v_mul_f32_e32 v102, 0xbfb8aa3b, v102
	v_mul_f32_e32 v103, 0xbfb8aa3b, v103
	v_mul_f32_e32 v104, 0xbfb8aa3b, v104
	v_mul_f32_e32 v105, 0xbfb8aa3b, v105
	v_mul_f32_e32 v70, 0xbfb8aa3b, v70
	v_mul_f32_e32 v71, 0xbfb8aa3b, v71
	v_mul_f32_e32 v72, 0xbfb8aa3b, v72
	v_mul_f32_e32 v73, 0xbfb8aa3b, v73
	v_exp_f32_e32 v102, v102
	v_exp_f32_e32 v103, v103
	v_exp_f32_e32 v104, v104
	v_exp_f32_e32 v105, v105
	v_exp_f32_e32 v70, v70
	v_exp_f32_e32 v71, v71
	v_exp_f32_e32 v72, v72
	v_exp_f32_e32 v73, v73
	v_add_f32_e32 v102, 1.0, v102
	v_add_f32_e32 v103, 1.0, v103
	v_add_f32_e32 v104, 1.0, v104
	v_add_f32_e32 v105, 1.0, v105
	v_add_f32_e32 v70, 1.0, v70
	v_add_f32_e32 v71, 1.0, v71
	v_add_f32_e32 v72, 1.0, v72
	v_add_f32_e32 v73, 1.0, v73
	v_rcp_f32_e32 v102, v102
	v_rcp_f32_e32 v103, v103
	v_rcp_f32_e32 v104, v104
	v_rcp_f32_e32 v105, v105
	v_rcp_f32_e32 v70, v70
	v_rcp_f32_e32 v71, v71
	v_rcp_f32_e32 v72, v72
	v_rcp_f32_e32 v73, v73
	v_add_f32_e32 v38, v38, v168
	v_add_f32_e32 v39, v39, v169
	v_add_f32_e32 v40, v40, v170
	v_add_f32_e32 v41, v41, v171
	v_add_f32_e32 v6, v6, v172
	v_add_f32_e32 v7, v7, v173
	v_add_f32_e32 v8, v8, v174
	v_add_f32_e32 v9, v9, v175
	v_mul_f32_e32 v38, 0xbfb8aa3b, v38
	v_mul_f32_e32 v39, 0xbfb8aa3b, v39
	v_mul_f32_e32 v40, 0xbfb8aa3b, v40
	v_mul_f32_e32 v41, 0xbfb8aa3b, v41
	v_mul_f32_e32 v6, 0xbfb8aa3b, v6
	v_mul_f32_e32 v7, 0xbfb8aa3b, v7
	v_mul_f32_e32 v8, 0xbfb8aa3b, v8
	v_mul_f32_e32 v9, 0xbfb8aa3b, v9
	v_exp_f32_e32 v38, v38
	v_exp_f32_e32 v39, v39
	v_exp_f32_e32 v40, v40
	v_exp_f32_e32 v41, v41
	v_exp_f32_e32 v6, v6
	v_exp_f32_e32 v7, v7
	v_exp_f32_e32 v8, v8
	v_exp_f32_e32 v9, v9
	v_add_f32_e32 v38, 1.0, v38
	v_add_f32_e32 v39, 1.0, v39
	v_add_f32_e32 v40, 1.0, v40
	v_add_f32_e32 v41, 1.0, v41
	v_add_f32_e32 v6, 1.0, v6
	v_add_f32_e32 v7, 1.0, v7
	v_add_f32_e32 v8, 1.0, v8
	v_add_f32_e32 v9, 1.0, v9
	v_rcp_f32_e32 v38, v38
	v_rcp_f32_e32 v39, v39
	v_rcp_f32_e32 v40, v40
	v_rcp_f32_e32 v41, v41
	v_rcp_f32_e32 v6, v6
	v_rcp_f32_e32 v7, v7
	v_rcp_f32_e32 v8, v8
	v_rcp_f32_e32 v9, v9
	v_cvt_pk_bf16_f32 v102, v102, v103
	v_cvt_pk_bf16_f32 v103, v104, v105
	v_cvt_pk_bf16_f32 v104, v70, v71
	v_cvt_pk_bf16_f32 v105, v72, v73
	v_cvt_pk_bf16_f32 v38, v38, v39
	v_cvt_pk_bf16_f32 v39, v40, v41
	v_cvt_pk_bf16_f32 v40, v6, v7
	v_cvt_pk_bf16_f32 v41, v8, v9
	v_permlane16_swap_b32_e32 v102, v104
	v_permlane16_swap_b32_e32 v103, v105
	v_permlane16_swap_b32_e32 v38, v40
	v_permlane16_swap_b32_e32 v39, v41
	global_store_dwordx4 v[154:155], v[102:105], off offset:0
	global_store_dwordx4 v[154:155], v[38:41], off offset:256
	s_mul_i32 s42, s52, 176
	v_lshl_add_u64 v[156:157], v[152:153], 0, s[42:43]
	v_add_f32_e32 v98, v98, v160
	v_add_f32_e32 v99, v99, v161
	v_add_f32_e32 v100, v100, v162
	v_add_f32_e32 v101, v101, v163
	v_add_f32_e32 v66, v66, v164
	v_add_f32_e32 v67, v67, v165
	v_add_f32_e32 v68, v68, v166
	v_add_f32_e32 v69, v69, v167
	v_mul_f32_e32 v98, 0xbfb8aa3b, v98
	v_mul_f32_e32 v99, 0xbfb8aa3b, v99
	v_mul_f32_e32 v100, 0xbfb8aa3b, v100
	v_mul_f32_e32 v101, 0xbfb8aa3b, v101
	v_mul_f32_e32 v66, 0xbfb8aa3b, v66
	v_mul_f32_e32 v67, 0xbfb8aa3b, v67
	v_mul_f32_e32 v68, 0xbfb8aa3b, v68
	v_mul_f32_e32 v69, 0xbfb8aa3b, v69
	v_exp_f32_e32 v98, v98
	v_exp_f32_e32 v99, v99
	v_exp_f32_e32 v100, v100
	v_exp_f32_e32 v101, v101
	v_exp_f32_e32 v66, v66
	v_exp_f32_e32 v67, v67
	v_exp_f32_e32 v68, v68
	v_exp_f32_e32 v69, v69
	v_add_f32_e32 v98, 1.0, v98
	v_add_f32_e32 v99, 1.0, v99
	v_add_f32_e32 v100, 1.0, v100
	v_add_f32_e32 v101, 1.0, v101
	v_add_f32_e32 v66, 1.0, v66
	v_add_f32_e32 v67, 1.0, v67
	v_add_f32_e32 v68, 1.0, v68
	v_add_f32_e32 v69, 1.0, v69
	v_rcp_f32_e32 v98, v98
	v_rcp_f32_e32 v99, v99
	v_rcp_f32_e32 v100, v100
	v_rcp_f32_e32 v101, v101
	v_rcp_f32_e32 v66, v66
	v_rcp_f32_e32 v67, v67
	v_rcp_f32_e32 v68, v68
	v_rcp_f32_e32 v69, v69
	v_add_f32_e32 v34, v34, v168
	v_add_f32_e32 v35, v35, v169
	v_add_f32_e32 v36, v36, v170
	v_add_f32_e32 v37, v37, v171
	v_add_f32_e32 v2, v2, v172
	v_add_f32_e32 v3, v3, v173
	v_add_f32_e32 v4, v4, v174
	v_add_f32_e32 v5, v5, v175
	v_mul_f32_e32 v34, 0xbfb8aa3b, v34
	v_mul_f32_e32 v35, 0xbfb8aa3b, v35
	v_mul_f32_e32 v36, 0xbfb8aa3b, v36
	v_mul_f32_e32 v37, 0xbfb8aa3b, v37
	v_mul_f32_e32 v2, 0xbfb8aa3b, v2
	v_mul_f32_e32 v3, 0xbfb8aa3b, v3
	v_mul_f32_e32 v4, 0xbfb8aa3b, v4
	v_mul_f32_e32 v5, 0xbfb8aa3b, v5
	v_exp_f32_e32 v34, v34
	v_exp_f32_e32 v35, v35
	v_exp_f32_e32 v36, v36
	v_exp_f32_e32 v37, v37
	v_exp_f32_e32 v2, v2
	v_exp_f32_e32 v3, v3
	v_exp_f32_e32 v4, v4
	v_exp_f32_e32 v5, v5
	v_add_f32_e32 v34, 1.0, v34
	v_add_f32_e32 v35, 1.0, v35
	v_add_f32_e32 v36, 1.0, v36
	v_add_f32_e32 v37, 1.0, v37
	v_add_f32_e32 v2, 1.0, v2
	v_add_f32_e32 v3, 1.0, v3
	v_add_f32_e32 v4, 1.0, v4
	v_add_f32_e32 v5, 1.0, v5
	v_rcp_f32_e32 v34, v34
	v_rcp_f32_e32 v35, v35
	v_rcp_f32_e32 v36, v36
	v_rcp_f32_e32 v37, v37
	v_rcp_f32_e32 v2, v2
	v_rcp_f32_e32 v3, v3
	v_rcp_f32_e32 v4, v4
	v_rcp_f32_e32 v5, v5
	v_cvt_pk_bf16_f32 v98, v98, v99
	v_cvt_pk_bf16_f32 v99, v100, v101
	v_cvt_pk_bf16_f32 v100, v66, v67
	v_cvt_pk_bf16_f32 v101, v68, v69
	v_cvt_pk_bf16_f32 v34, v34, v35
	v_cvt_pk_bf16_f32 v35, v36, v37
	v_cvt_pk_bf16_f32 v36, v2, v3
	v_cvt_pk_bf16_f32 v37, v4, v5
	v_permlane16_swap_b32_e32 v98, v100
	v_permlane16_swap_b32_e32 v99, v101
	v_permlane16_swap_b32_e32 v34, v36
	v_permlane16_swap_b32_e32 v35, v37
	global_store_dwordx4 v[156:157], v[98:101], off offset:0
	global_store_dwordx4 v[156:157], v[34:37], off offset:256
	s_branch .LBB0_986

.Lipf_ct:
	v_lshrrev_b32_e32 v178, 8, v211
	v_and_b32_e32 v179, 15, v219
	v_readfirstlane_b32 s82, v178
	v_cmp_le_u32_e64 s[48:49], 13, v179
	v_subrev_u32_e32 v179, 13, v179
	v_mul_u32_u24_e32 v179, 0x1800, v179
	v_add_u32_e32 v178, s45, v135
	v_lshl_add_u32 v180, v178, 2, v179
	v_mov_b32_e32 v181, 0
	s_cmp_eq_u32 s62, 2
	s_cbranch_scc1 .Lipf_ct_smp
	s_lshr_b32 s63, s81, 4
	s_sub_u32 s63, s63, 11
	v_lshl_add_u64 v[180:181], v[180:181], 0, s[34:35]
	s_branch .Lipf_ct_go
.Lipf_ct_smp:
	s_sub_u32 s63, s81, 0x80
	s_lshl_b32 s63, s63, 4
	s_lshl_b32 s0, s82, 2
	s_add_u32 s63, s63, s0
	v_lshl_add_u64 v[180:181], v[180:181], 0, s[38:39]
.Lipf_ct_go:
	s_cmp_eq_u32 s62, 2
	s_cbranch_scc0 .Lct_skip_0
	s_add_u32 s42, s63, 0
	s_mul_i32 s42, s42, 0x4800
	v_lshl_add_u64 v[182:183], v[180:181], 0, s[42:43]
	s_mov_b64 exec, s[48:49]
	global_store_dwordx4 v[182:183], v[130:133], off offset:0
	global_store_dwordx4 v[182:183], v[94:97], off offset:64
	global_store_dwordx4 v[182:183], v[62:65], off offset:512
	global_store_dwordx4 v[182:183], v[30:33], off offset:576
	s_mov_b64 exec, -1
.Lct_skip_0:
	v_mov_b32_e32 v154, v152
	v_mov_b32_e32 v155, v153
	v_cvt_pk_bf16_f32 v130, v130, v131
	v_cvt_pk_bf16_f32 v131, v132, v133
	v_cvt_pk_bf16_f32 v132, v94, v95
	v_cvt_pk_bf16_f32 v133, v96, v97
	v_cvt_pk_bf16_f32 v62, v62, v63
	v_cvt_pk_bf16_f32 v63, v64, v65
	v_cvt_pk_bf16_f32 v64, v30, v31
	v_cvt_pk_bf16_f32 v65, v32, v33
	v_permlane16_swap_b32_e32 v130, v132
	v_permlane16_swap_b32_e32 v131, v133
	v_permlane16_swap_b32_e32 v62, v64
	v_permlane16_swap_b32_e32 v63, v65
	global_store_dwordx4 v[154:155], v[130:133], off offset:0
	global_store_dwordx4 v[154:155], v[62:65], off offset:256
	s_cmp_eq_u32 s62, 2
	s_cbranch_scc0 .Lct_skip_1
	s_add_u32 s42, s63, 1
	s_mul_i32 s42, s42, 0x4800
	v_lshl_add_u64 v[182:183], v[180:181], 0, s[42:43]
	s_mov_b64 exec, s[48:49]
	global_store_dwordx4 v[182:183], v[126:129], off offset:0
	global_store_dwordx4 v[182:183], v[90:93], off offset:64
	global_store_dwordx4 v[182:183], v[58:61], off offset:512
	global_store_dwordx4 v[182:183], v[26:29], off offset:576
	s_mov_b64 exec, -1
.Lct_skip_1:
	s_mul_i32 s42, s52, 16
	v_lshl_add_u64 v[156:157], v[152:153], 0, s[42:43]
	v_cvt_pk_bf16_f32 v126, v126, v127
	v_cvt_pk_bf16_f32 v127, v128, v129
	v_cvt_pk_bf16_f32 v128, v90, v91
	v_cvt_pk_bf16_f32 v129, v92, v93
	v_cvt_pk_bf16_f32 v58, v58, v59
	v_cvt_pk_bf16_f32 v59, v60, v61
	v_cvt_pk_bf16_f32 v60, v26, v27
	v_cvt_pk_bf16_f32 v61, v28, v29
	v_permlane16_swap_b32_e32 v126, v128
	v_permlane16_swap_b32_e32 v127, v129
	v_permlane16_swap_b32_e32 v58, v60
	v_permlane16_swap_b32_e32 v59, v61
	global_store_dwordx4 v[156:157], v[126:129], off offset:0
	global_store_dwordx4 v[156:157], v[58:61], off offset:256
	s_cmp_eq_u32 s62, 2
	s_cbranch_scc0 .Lct_skip_2
	s_add_u32 s42, s63, 2
	s_mul_i32 s42, s42, 0x4800
	v_lshl_add_u64 v[182:183], v[180:181], 0, s[42:43]
	s_mov_b64 exec, s[48:49]
	global_store_dwordx4 v[182:183], v[122:125], off offset:0
	global_store_dwordx4 v[182:183], v[86:89], off offset:64
	global_store_dwordx4 v[182:183], v[54:57], off offset:512
	global_store_dwordx4 v[182:183], v[22:25], off offset:576
	s_mov_b64 exec, -1
.Lct_skip_2:
	s_mul_i32 s42, s52, 32
	v_lshl_add_u64 v[154:155], v[152:153], 0, s[42:43]
	v_cvt_pk_bf16_f32 v122, v122, v123
	v_cvt_pk_bf16_f32 v123, v124, v125
	v_cvt_pk_bf16_f32 v124, v86, v87
	v_cvt_pk_bf16_f32 v125, v88, v89
	v_cvt_pk_bf16_f32 v54, v54, v55
	v_cvt_pk_bf16_f32 v55, v56, v57
	v_cvt_pk_bf16_f32 v56, v22, v23
	v_cvt_pk_bf16_f32 v57, v24, v25
	v_permlane16_swap_b32_e32 v122, v124
	v_permlane16_swap_b32_e32 v123, v125
	v_permlane16_swap_b32_e32 v54, v56
	v_permlane16_swap_b32_e32 v55, v57
	global_store_dwordx4 v[154:155], v[122:125], off offset:0
	global_store_dwordx4 v[154:155], v[54:57], off offset:256
	s_cmp_eq_u32 s62, 2
	s_cbranch_scc0 .Lct_skip_3
	s_add_u32 s42, s63, 3
	s_mul_i32 s42, s42, 0x4800
	v_lshl_add_u64 v[182:183], v[180:181], 0, s[42:43]
	s_mov_b64 exec, s[48:49]
	global_store_dwordx4 v[182:183], v[118:121], off offset:0
	global_store_dwordx4 v[182:183], v[82:85], off offset:64
	global_store_dwordx4 v[182:183], v[50:53], off offset:512
	global_store_dwordx4 v[182:183], v[18:21], off offset:576
	s_mov_b64 exec, -1
.Lct_skip_3:
	s_mul_i32 s42, s52, 48
	v_lshl_add_u64 v[156:157], v[152:153], 0, s[42:43]
	v_cvt_pk_bf16_f32 v118, v118, v119
	v_cvt_pk_bf16_f32 v119, v120, v121
	v_cvt_pk_bf16_f32 v120, v82, v83
	v_cvt_pk_bf16_f32 v121, v84, v85
	v_cvt_pk_bf16_f32 v50, v50, v51
	v_cvt_pk_bf16_f32 v51, v52, v53
	v_cvt_pk_bf16_f32 v52, v18, v19
	v_cvt_pk_bf16_f32 v53, v20, v21
	v_permlane16_swap_b32_e32 v118, v120
	v_permlane16_swap_b32_e32 v119, v121
	v_permlane16_swap_b32_e32 v50, v52
	v_permlane16_swap_b32_e32 v51, v53
	global_store_dwordx4 v[156:157], v[118:121], off offset:0
	global_store_dwordx4 v[156:157], v[50:53], off offset:256
	s_cmp_eq_u32 s62, 2
	s_cbranch_scc0 .Lct_skip_8
	s_add_u32 s42, s63, 8
	s_mul_i32 s42, s42, 0x4800
	v_lshl_add_u64 v[182:183], v[180:181], 0, s[42:43]
	s_mov_b64 exec, s[48:49]
	global_store_dwordx4 v[182:183], v[114:117], off offset:0
	global_store_dwordx4 v[182:183], v[78:81], off offset:64
	global_store_dwordx4 v[182:183], v[46:49], off offset:512
	global_store_dwordx4 v[182:183], v[14:17], off offset:576
	s_mov_b64 exec, -1
.Lct_skip_8:
	s_mul_i32 s42, s52, 128
	v_lshl_add_u64 v[154:155], v[152:153], 0, s[42:43]
	v_cvt_pk_bf16_f32 v114, v114, v115
	v_cvt_pk_bf16_f32 v115, v116, v117
	v_cvt_pk_bf16_f32 v116, v78, v79
	v_cvt_pk_bf16_f32 v117, v80, v81
	v_cvt_pk_bf16_f32 v46, v46, v47
	v_cvt_pk_bf16_f32 v47, v48, v49
	v_cvt_pk_bf16_f32 v48, v14, v15
	v_cvt_pk_bf16_f32 v49, v16, v17
	v_permlane16_swap_b32_e32 v114, v116
	v_permlane16_swap_b32_e32 v115, v117
	v_permlane16_swap_b32_e32 v46, v48
	v_permlane16_swap_b32_e32 v47, v49
	global_store_dwordx4 v[154:155], v[114:117], off offset:0
	global_store_dwordx4 v[154:155], v[46:49], off offset:256
	s_cmp_eq_u32 s62, 2
	s_cbranch_scc0 .Lct_skip_9
	s_add_u32 s42, s63, 9
	s_mul_i32 s42, s42, 0x4800
	v_lshl_add_u64 v[182:183], v[180:181], 0, s[42:43]
	s_mov_b64 exec, s[48:49]
	global_store_dwordx4 v[182:183], v[106:109], off offset:0
	global_store_dwordx4 v[182:183], v[74:77], off offset:64
	global_store_dwordx4 v[182:183], v[42:45], off offset:512
	global_store_dwordx4 v[182:183], v[10:13], off offset:576
	s_mov_b64 exec, -1
.Lct_skip_9:
	s_mul_i32 s42, s52, 144
	v_lshl_add_u64 v[156:157], v[152:153], 0, s[42:43]
	v_cvt_pk_bf16_f32 v106, v106, v107
	v_cvt_pk_bf16_f32 v107, v108, v109
	v_cvt_pk_bf16_f32 v108, v74, v75
	v_cvt_pk_bf16_f32 v109, v76, v77
	v_cvt_pk_bf16_f32 v42, v42, v43
	v_cvt_pk_bf16_f32 v43, v44, v45
	v_cvt_pk_bf16_f32 v44, v10, v11
	v_cvt_pk_bf16_f32 v45, v12, v13
	v_permlane16_swap_b32_e32 v106, v108
	v_permlane16_swap_b32_e32 v107, v109
	v_permlane16_swap_b32_e32 v42, v44
	v_permlane16_swap_b32_e32 v43, v45
	global_store_dwordx4 v[156:157], v[106:109], off offset:0
	global_store_dwordx4 v[156:157], v[42:45], off offset:256
	s_cmp_eq_u32 s62, 2
	s_cbranch_scc0 .Lct_skip_10
	s_add_u32 s42, s63, 10
	s_mul_i32 s42, s42, 0x4800
	v_lshl_add_u64 v[182:183], v[180:181], 0, s[42:43]
	s_mov_b64 exec, s[48:49]
	global_store_dwordx4 v[182:183], v[102:105], off offset:0
	global_store_dwordx4 v[182:183], v[70:73], off offset:64
	global_store_dwordx4 v[182:183], v[38:41], off offset:512
	global_store_dwordx4 v[182:183], v[6:9], off offset:576
	s_mov_b64 exec, -1
.Lct_skip_10:
	s_mul_i32 s42, s52, 160
	v_lshl_add_u64 v[154:155], v[152:153], 0, s[42:43]
	v_cvt_pk_bf16_f32 v102, v102, v103
	v_cvt_pk_bf16_f32 v103, v104, v105
	v_cvt_pk_bf16_f32 v104, v70, v71
	v_cvt_pk_bf16_f32 v105, v72, v73
	v_cvt_pk_bf16_f32 v38, v38, v39
	v_cvt_pk_bf16_f32 v39, v40, v41
	v_cvt_pk_bf16_f32 v40, v6, v7
	v_cvt_pk_bf16_f32 v41, v8, v9
	v_permlane16_swap_b32_e32 v102, v104
	v_permlane16_swap_b32_e32 v103, v105
	v_permlane16_swap_b32_e32 v38, v40
	v_permlane16_swap_b32_e32 v39, v41
	global_store_dwordx4 v[154:155], v[102:105], off offset:0
	global_store_dwordx4 v[154:155], v[38:41], off offset:256
	s_cmp_eq_u32 s62, 2
	s_cbranch_scc1 .Lct_do_11
	s_cmp_eq_u32 s82, 1
	s_cbranch_scc0 .Lct_skip_11
.Lct_do_11:
	s_add_u32 s42, s63, 11
	s_mul_i32 s42, s42, 0x4800
	v_lshl_add_u64 v[182:183], v[180:181], 0, s[42:43]
	s_mov_b64 exec, s[48:49]
	global_store_dwordx4 v[182:183], v[98:101], off offset:0
	global_store_dwordx4 v[182:183], v[66:69], off offset:64
	global_store_dwordx4 v[182:183], v[34:37], off offset:512
	global_store_dwordx4 v[182:183], v[2:5], off offset:576
	s_mov_b64 exec, -1
.Lct_skip_11:
	s_mul_i32 s42, s52, 176
	v_lshl_add_u64 v[156:157], v[152:153], 0, s[42:43]
	v_cvt_pk_bf16_f32 v98, v98, v99
	v_cvt_pk_bf16_f32 v99, v100, v101
	v_cvt_pk_bf16_f32 v100, v66, v67
	v_cvt_pk_bf16_f32 v101, v68, v69
	v_cvt_pk_bf16_f32 v34, v34, v35
	v_cvt_pk_bf16_f32 v35, v36, v37
	v_cvt_pk_bf16_f32 v36, v2, v3
	v_cvt_pk_bf16_f32 v37, v4, v5
	v_permlane16_swap_b32_e32 v98, v100
	v_permlane16_swap_b32_e32 v99, v101
	v_permlane16_swap_b32_e32 v34, v36
	v_permlane16_swap_b32_e32 v35, v37
	global_store_dwordx4 v[156:157], v[98:101], off offset:0
	global_store_dwordx4 v[156:157], v[34:37], off offset:256
	s_branch .LBB0_986
